# v043 with LRU-wave priority restored to the original 1/0 scheme (rebalance after SSD trims)
# baseline (speedup 1.0000x reference)
.LBB0_587:
	v_mov_b32_e32 v108, v182
	s_bitcmp1_b32 s21, 0
	s_cselect_b32 s21, 0xe000, 0
	v_bfe_u32 v109, v108, 3, 2
	v_and_or_b32 v0, v108, 4, v109
	v_and_b32_e32 v1, 3, v108
	s_add_i32 s21, s21, 0
	v_and_b32_e32 v102, 31, v108
	v_ashrrev_i32_e32 v103, 5, v108
	v_lshl_or_b32 v110, v0, 2, v1
	s_setprio 1
	v_lshl_add_u32 v111, v110, 8, s21
	s_waitcnt lgkmcnt(0)
	v_bitop3_b32 v248, v110, v103, 15 bitop3:0x6c
	v_lshl_add_u32 v248, v248, 4, v111
	ds_read_b128 v[216:219], v248 offset:24576
	v_add_u32_e32 v248, 2, v103
	v_bitop3_b32 v248, v110, v248, 15 bitop3:0x6c
	v_lshl_add_u32 v248, v248, 4, v111
	ds_read_b128 v[220:223], v248 offset:24576
	v_add_u32_e32 v248, 4, v103
	v_bitop3_b32 v248, v110, v248, 15 bitop3:0x6c
	v_lshl_add_u32 v248, v248, 4, v111
	ds_read_b128 v[224:227], v248 offset:24576
	v_add_u32_e32 v248, 6, v103
	v_bitop3_b32 v248, v110, v248, 15 bitop3:0x6c
	v_lshl_add_u32 v248, v248, 4, v111
	ds_read_b128 v[228:231], v248 offset:24576
	v_add_u32_e32 v248, 8, v103
	v_bitop3_b32 v248, v110, v248, 15 bitop3:0x6c
	v_lshl_add_u32 v248, v248, 4, v111
	ds_read_b128 v[232:235], v248 offset:24576
	v_add_u32_e32 v248, 10, v103
	v_bitop3_b32 v248, v110, v248, 15 bitop3:0x6c
	v_lshl_add_u32 v248, v248, 4, v111
	ds_read_b128 v[236:239], v248 offset:24576
	v_add_u32_e32 v248, 12, v103
	v_bitop3_b32 v248, v110, v248, 15 bitop3:0x6c
	v_lshl_add_u32 v248, v248, 4, v111
	ds_read_b128 v[240:243], v248 offset:24576
	v_add_u32_e32 v248, 14, v103
	v_bitop3_b32 v248, v110, v248, 15 bitop3:0x6c
	v_lshl_add_u32 v248, v248, 4, v111
	ds_read_b128 v[244:247], v248 offset:24576
	s_waitcnt lgkmcnt(7)
	v_mfma_f32_32x32x16_bf16 v[16:31], v[216:219], v[32:35], 0
	v_mfma_f32_32x32x16_bf16 v[0:15], v[216:219], v[64:67], 0
	s_waitcnt lgkmcnt(6)
	v_mfma_f32_32x32x16_bf16 v[16:31], v[220:223], v[36:39], v[16:31]
	v_mfma_f32_32x32x16_bf16 v[0:15], v[220:223], v[68:71], v[0:15]
	s_waitcnt lgkmcnt(5)
	v_mfma_f32_32x32x16_bf16 v[16:31], v[224:227], v[40:43], v[16:31]
	v_mfma_f32_32x32x16_bf16 v[0:15], v[224:227], v[72:75], v[0:15]
	s_waitcnt lgkmcnt(4)
	v_mfma_f32_32x32x16_bf16 v[16:31], v[228:231], v[44:47], v[16:31]
	v_mfma_f32_32x32x16_bf16 v[0:15], v[228:231], v[76:79], v[0:15]
	s_waitcnt lgkmcnt(3)
	v_mfma_f32_32x32x16_bf16 v[16:31], v[232:235], v[48:51], v[16:31]
	v_mfma_f32_32x32x16_bf16 v[0:15], v[232:235], v[80:83], v[0:15]
	s_waitcnt lgkmcnt(2)
	v_mfma_f32_32x32x16_bf16 v[16:31], v[236:239], v[52:55], v[16:31]
	v_mfma_f32_32x32x16_bf16 v[0:15], v[236:239], v[84:87], v[0:15]
	s_waitcnt lgkmcnt(1)
	v_mfma_f32_32x32x16_bf16 v[16:31], v[240:243], v[56:59], v[16:31]
	v_mfma_f32_32x32x16_bf16 v[0:15], v[240:243], v[88:91], v[0:15]
	s_waitcnt lgkmcnt(0)
	v_mfma_f32_32x32x16_bf16 v[16:31], v[244:247], v[60:63], v[16:31]
	v_mfma_f32_32x32x16_bf16 v[0:15], v[244:247], v[92:95], v[0:15]
	s_setprio 0
	s_nop 9
	v_fmamk_f32 v16, v16, 0xbfb8aa3b, v100
	v_exp_f32_e32 v16, v16
	v_fmamk_f32 v0, v0, 0xbfb8aa3b, v101
	v_exp_f32_e32 v0, v0
	v_fmamk_f32 v17, v17, 0xbfb8aa3b, v100
	v_add_f32_e32 v16, 1.0, v16
	v_rcp_f32_e32 v16, v16
	v_exp_f32_e32 v17, v17
	v_lshlrev_b32_e32 v105, 1, v108
	v_cmp_gt_u32_e32 vcc, 32, v108
	v_mul_f32_e32 v16, v99, v16
	v_exp_f32_e32 v16, v16
	v_lshlrev_b32_e32 v106, 4, v109
	v_mov_b32_e32 v108, s88
	s_movk_i32 s25, 0x50
	v_fma_f32 v116, -v16, v16, 1.0
	v_bitop3_b32 v113, v106, s25, v108 bitop3:0x36
	s_movk_i32 s25, 0x60
	v_add_f32_e32 v0, 1.0, v0
	v_sqrt_f32_e32 v116, v116
	v_bitop3_b32 v114, v106, s25, v108 bitop3:0x36
	s_movk_i32 s25, 0x70
	v_rcp_f32_e32 v0, v0
	v_add_f32_e32 v17, 1.0, v17
	v_fmamk_f32 v1, v1, 0xbfb8aa3b, v101
	v_fmamk_f32 v18, v18, 0xbfb8aa3b, v100
	v_lshl_add_u32 v104, v103, 12, s21
	v_and_b32_e32 v105, 14, v105
	v_or_b32_e32 v107, s88, v106
	v_bitop3_b32 v109, v106, 16, s88 bitop3:0x36
	v_bitop3_b32 v110, v106, 32, s88 bitop3:0x36
	v_bitop3_b32 v111, v106, 48, s88 bitop3:0x36
	v_bitop3_b32 v112, v106, 64, s88 bitop3:0x36
	v_bitop3_b32 v115, v106, s25, v108 bitop3:0x36
	s_and_b64 s[4:5], s[22:23], s[4:5]
	v_exp_f32_e32 v1, v1
	v_rcp_f32_e32 v117, v17
	v_exp_f32_e32 v18, v18
	v_add3_u32 v107, v104, v107, v105
	v_add3_u32 v109, v104, v109, v105
	v_add3_u32 v110, v104, v110, v105
	v_add3_u32 v111, v104, v111, v105
	v_add3_u32 v112, v104, v112, v105
	v_add3_u32 v113, v104, v113, v105
	v_add3_u32 v114, v104, v114, v105
	v_add3_u32 v115, v104, v115, v105
	s_and_b64 s[4:5], s[4:5], vcc
	ds_read_u16 v107, v107 offset:24576
	ds_read_u16 v109, v109 offset:24832
	ds_read_u16 v110, v110 offset:25088
	ds_read_u16 v111, v111 offset:25344
	ds_read_u16 v112, v112 offset:25600
	ds_read_u16 v113, v113 offset:25856
	ds_read_u16 v114, v114 offset:26112
	ds_read_u16 v115, v115 offset:26368
	v_cndmask_b32_e64 v116, v116, 1.0, s[4:5]
	s_waitcnt lgkmcnt(0)
	v_lshlrev_b32_e32 v107, 16, v107
	v_mul_f32_e32 v0, v0, v116
	v_mul_f32_e32 v17, v0, v107
	v_add_f32_e32 v0, 1.0, v1
	v_mul_f32_e32 v1, v99, v117
	v_add_f32_e32 v18, 1.0, v18
	v_fmamk_f32 v19, v19, 0xbfb8aa3b, v100
	v_exp_f32_e32 v1, v1
	v_rcp_f32_e32 v18, v18
	v_exp_f32_e32 v19, v19
	v_fmamk_f32 v2, v2, 0xbfb8aa3b, v101
	v_fma_f32 v107, -v1, v1, 1.0
	v_mul_f32_e32 v18, v99, v18
	v_add_f32_e32 v19, 1.0, v19
	v_fmamk_f32 v20, v20, 0xbfb8aa3b, v100
	v_rcp_f32_e32 v0, v0
	v_sqrt_f32_e32 v107, v107
	v_exp_f32_e32 v2, v2
	v_exp_f32_e32 v18, v18
	v_rcp_f32_e32 v19, v19
	v_exp_f32_e32 v20, v20
	v_mul_f32_e32 v0, v0, v107
	v_add_f32_e32 v2, 1.0, v2
	v_fma_f32 v107, -v18, v18, 1.0
	v_fmamk_f32 v3, v3, 0xbfb8aa3b, v101
	v_mul_f32_e32 v19, v99, v19
	v_add_f32_e32 v20, 1.0, v20
	v_fmamk_f32 v21, v21, 0xbfb8aa3b, v100
	v_rcp_f32_e32 v2, v2
	v_sqrt_f32_e32 v107, v107
	v_exp_f32_e32 v3, v3
	v_exp_f32_e32 v19, v19
	v_rcp_f32_e32 v20, v20
	v_exp_f32_e32 v21, v21
	v_mul_f32_e32 v2, v2, v107
	v_add_f32_e32 v3, 1.0, v3
	v_fma_f32 v107, -v19, v19, 1.0
	v_fmamk_f32 v4, v4, 0xbfb8aa3b, v101
	v_mul_f32_e32 v20, v99, v20
	v_add_f32_e32 v21, 1.0, v21
	v_fmamk_f32 v22, v22, 0xbfb8aa3b, v100
	v_rcp_f32_e32 v3, v3
	v_sqrt_f32_e32 v107, v107
	v_exp_f32_e32 v4, v4
	v_exp_f32_e32 v20, v20
	v_rcp_f32_e32 v21, v21
	v_exp_f32_e32 v22, v22
	v_fmamk_f32 v23, v23, 0xbfb8aa3b, v100
	v_exp_f32_e32 v23, v23
	v_mul_f32_e32 v3, v3, v107
	v_add_f32_e32 v4, 1.0, v4
	v_fma_f32 v107, -v20, v20, 1.0
	v_fmamk_f32 v5, v5, 0xbfb8aa3b, v101
	v_mul_f32_e32 v21, v99, v21
	v_add_f32_e32 v22, 1.0, v22
	v_rcp_f32_e32 v4, v4
	v_sqrt_f32_e32 v107, v107
	v_exp_f32_e32 v5, v5
	v_exp_f32_e32 v21, v21
	v_rcp_f32_e32 v22, v22
	v_add_f32_e32 v23, 1.0, v23
	v_rcp_f32_e32 v23, v23
	v_mul_f32_e32 v4, v4, v107
	v_lshlrev_b32_e32 v107, 16, v113
	v_add_f32_e32 v5, 1.0, v5
	v_fma_f32 v113, -v21, v21, 1.0
	v_fmamk_f32 v6, v6, 0xbfb8aa3b, v101
	v_mul_f32_e32 v22, v99, v22
	v_rcp_f32_e32 v5, v5
	v_sqrt_f32_e32 v113, v113
	v_exp_f32_e32 v6, v6
	v_exp_f32_e32 v22, v22
	v_fmamk_f32 v7, v7, 0xbfb8aa3b, v101
	v_mul_f32_e32 v23, v99, v23
	v_exp_f32_e32 v7, v7
	v_exp_f32_e32 v23, v23
	v_fmamk_f32 v24, v24, 0xbfb8aa3b, v100
	v_mul_f32_e32 v5, v5, v113
	v_add_f32_e32 v6, 1.0, v6
	v_fma_f32 v113, -v22, v22, 1.0
	v_exp_f32_e32 v24, v24
	v_rcp_f32_e32 v6, v6
	v_sqrt_f32_e32 v113, v113
	v_add_f32_e32 v7, 1.0, v7
	v_fma_f32 v116, -v23, v23, 1.0
	v_rcp_f32_e32 v7, v7
	v_sqrt_f32_e32 v116, v116
	s_movk_i32 s4, 0x80
	v_add_f32_e32 v24, 1.0, v24
	v_mul_f32_e32 v6, v6, v113
	v_lshlrev_b32_e32 v113, 16, v115
	v_bitop3_b32 v115, v106, s4, v108 bitop3:0x36
	s_movk_i32 s4, 0x90
	v_rcp_f32_e32 v24, v24
	v_mul_f32_e32 v7, v7, v116
	v_bitop3_b32 v116, v106, s4, v108 bitop3:0x36
	s_movk_i32 s4, 0xa0
	v_bitop3_b32 v117, v106, s4, v108 bitop3:0x36
	s_movk_i32 s4, 0xb0
	v_bitop3_b32 v118, v106, s4, v108 bitop3:0x36
	s_movk_i32 s4, 0xc0
	v_fmamk_f32 v8, v8, 0xbfb8aa3b, v101
	v_bitop3_b32 v119, v106, s4, v108 bitop3:0x36
	s_movk_i32 s4, 0xd0
	v_mul_f32_e32 v24, v99, v24
	v_exp_f32_e32 v8, v8
	v_bitop3_b32 v120, v106, s4, v108 bitop3:0x36
	s_movk_i32 s4, 0xe0
	v_fmamk_f32 v25, v25, 0xbfb8aa3b, v100
	v_exp_f32_e32 v24, v24
	v_bitop3_b32 v121, v106, s4, v108 bitop3:0x36
	s_movk_i32 s4, 0xf0
	v_exp_f32_e32 v25, v25
	v_bitop3_b32 v106, v106, s4, v108 bitop3:0x36
	v_add3_u32 v115, v104, v115, v105
	v_add3_u32 v116, v104, v116, v105
	v_add3_u32 v117, v104, v117, v105
	v_add3_u32 v118, v104, v118, v105
	v_add3_u32 v119, v104, v119, v105
	v_add3_u32 v120, v104, v120, v105
	v_add3_u32 v121, v104, v121, v105
	v_add3_u32 v104, v104, v106, v105
	ds_read_u16 v105, v115 offset:26624
	ds_read_u16 v106, v116 offset:26880
	ds_read_u16 v108, v117 offset:27136
	ds_read_u16 v115, v118 offset:27392
	ds_read_u16 v116, v119 offset:27648
	ds_read_u16 v117, v120 offset:27904
	ds_read_u16 v118, v121 offset:28160
	ds_read_u16 v104, v104 offset:28416
	v_add_f32_e32 v8, 1.0, v8
	v_fma_f32 v119, -v24, v24, 1.0
	v_fmamk_f32 v26, v26, 0xbfb8aa3b, v100
	v_rcp_f32_e32 v8, v8
	v_add_f32_e32 v25, 1.0, v25
	v_sqrt_f32_e32 v119, v119
	v_exp_f32_e32 v26, v26
	v_rcp_f32_e32 v25, v25
	v_fmamk_f32 v9, v9, 0xbfb8aa3b, v101
	v_mul_f32_e32 v119, v8, v119
	v_add_f32_e32 v8, 1.0, v26
	v_mul_f32_e32 v25, v99, v25
	v_rcp_f32_e32 v8, v8
	v_exp_f32_e32 v9, v9
	v_exp_f32_e32 v25, v25
	s_waitcnt lgkmcnt(0)
	v_lshlrev_b32_e32 v26, 16, v108
	v_mul_f32_e32 v8, v99, v8
	v_add_f32_e32 v9, 1.0, v9
	v_fma_f32 v120, -v25, v25, 1.0
	v_exp_f32_e32 v108, v8
	v_fmamk_f32 v8, v27, 0xbfb8aa3b, v100
	v_rcp_f32_e32 v9, v9
	v_sqrt_f32_e32 v120, v120
	v_exp_f32_e32 v8, v8
	v_fmamk_f32 v11, v11, 0xbfb8aa3b, v101
	v_exp_f32_e32 v11, v11
	v_mul_f32_e32 v120, v9, v120
	v_fmamk_f32 v9, v10, 0xbfb8aa3b, v101
	v_add_f32_e32 v8, 1.0, v8
	v_exp_f32_e32 v9, v9
	v_rcp_f32_e32 v8, v8
	v_fma_f32 v10, -v108, v108, 1.0
	v_sqrt_f32_e32 v10, v10
	v_add_f32_e32 v9, 1.0, v9
	v_mul_f32_e32 v8, v99, v8
	v_rcp_f32_e32 v9, v9
	v_exp_f32_e32 v27, v8
	v_add_f32_e32 v8, 1.0, v11
	v_rcp_f32_e32 v8, v8
	v_mul_f32_e32 v121, v9, v10
	v_fma_f32 v9, -v27, v27, 1.0
	v_fmamk_f32 v10, v28, 0xbfb8aa3b, v100
	v_sqrt_f32_e32 v9, v9
	v_exp_f32_e32 v10, v10
	v_fmamk_f32 v11, v13, 0xbfb8aa3b, v101
	v_exp_f32_e32 v11, v11
	v_mul_f32_e32 v28, v8, v9
	v_add_f32_e32 v9, 1.0, v10
	v_fmamk_f32 v10, v29, 0xbfb8aa3b, v100
	v_exp_f32_e32 v10, v10
	v_fmamk_f32 v8, v12, 0xbfb8aa3b, v101
	v_fmamk_f32 v13, v14, 0xbfb8aa3b, v101
	v_exp_f32_e32 v13, v13
	v_add_f32_e32 v10, 1.0, v10
	v_rcp_f32_e32 v12, v10
	v_add_f32_e32 v10, 1.0, v11
	v_fmamk_f32 v15, v15, 0xbfb8aa3b, v101
	v_exp_f32_e32 v15, v15
	v_mul_f32_e32 v11, v99, v12
	v_fmamk_f32 v12, v30, 0xbfb8aa3b, v100
	v_exp_f32_e32 v12, v12
	v_lshlrev_b32_e32 v109, 16, v109
	v_lshlrev_b32_e32 v110, 16, v110
	v_lshlrev_b32_e32 v29, 16, v117
	v_add_f32_e32 v12, 1.0, v12
	v_rcp_f32_e32 v14, v12
	v_add_f32_e32 v12, 1.0, v13
	v_lshlrev_b32_e32 v111, 16, v111
	v_lshlrev_b32_e32 v112, 16, v112
	v_mul_f32_e32 v13, v99, v14
	v_fmamk_f32 v14, v31, 0xbfb8aa3b, v100
	v_exp_f32_e32 v14, v14
	v_rcp_f32_e32 v9, v9
	v_lshlrev_b32_e32 v114, 16, v114
	v_exp_f32_e32 v8, v8
	v_add_f32_e32 v14, 1.0, v14
	v_rcp_f32_e32 v31, v14
	v_add_f32_e32 v14, 1.0, v15
	v_mul_f32_e32 v9, v99, v9
	v_exp_f32_e32 v9, v9
	v_mul_f32_e32 v15, v99, v31
	v_mul_f32_e32 v31, v1, v17
	v_fmac_f32_e32 v31, v0, v109
	v_mul_f32_e32 v117, v18, v31
	v_fmac_f32_e32 v117, v2, v110
	v_mul_f32_e32 v110, v19, v117
	v_fmac_f32_e32 v110, v3, v111
	v_mul_f32_e32 v111, v20, v110
	v_fmac_f32_e32 v111, v4, v112
	v_mul_f32_e32 v112, v21, v111
	v_fmac_f32_e32 v112, v5, v107
	v_mul_f32_e32 v107, v22, v112
	v_fmac_f32_e32 v107, v6, v114
	v_mul_f32_e32 v114, v23, v107
	v_fmac_f32_e32 v114, v7, v113
	v_lshlrev_b32_e32 v105, 16, v105
	v_mul_f32_e32 v113, v24, v114
	v_fmac_f32_e32 v113, v119, v105
	v_lshlrev_b32_e32 v106, 16, v106
	v_mul_f32_e32 v105, v25, v113
	v_add_f32_e32 v8, 1.0, v8
	v_fmac_f32_e32 v105, v120, v106
	v_fma_f32 v0, -v9, v9, 1.0
	v_rcp_f32_e32 v8, v8
	v_exp_f32_e32 v11, v11
	v_mul_f32_e32 v106, v108, v105
	v_sqrt_f32_e32 v6, v0
	v_fmac_f32_e32 v106, v121, v26
	v_lshlrev_b32_e32 v115, 16, v115
	v_mul_f32_e32 v7, v27, v106
	v_fmac_f32_e32 v7, v28, v115
	v_lshlrev_b32_e32 v116, 16, v116
	v_pk_mul_f32 v[2:3], v[8:9], v[6:7]
	v_fma_f32 v0, -v11, v11, 1.0
	v_rcp_f32_e32 v10, v10
	v_fmac_f32_e32 v3, v2, v116
	v_sqrt_f32_e32 v2, v0
	v_exp_f32_e32 v13, v13
	v_mul_f32_e32 v109, v1, v16
	v_mul_f32_e32 v18, v18, v109
	v_mul_f32_e32 v19, v19, v18
	v_mul_f32_e32 v20, v20, v19
	v_pk_mul_f32 v[0:1], v[10:11], v[2:3]
	v_mul_f32_e32 v21, v21, v20
	v_fmac_f32_e32 v1, v0, v29
	v_fma_f32 v0, -v13, v13, 1.0
	v_rcp_f32_e32 v12, v12
	v_exp_f32_e32 v15, v15
	v_mul_f32_e32 v6, v22, v21
	v_sqrt_f32_e32 v0, v0
	v_mul_f32_e32 v22, v23, v6
	v_mul_f32_e32 v23, v24, v22
	v_mul_f32_e32 v2, v25, v23
	v_lshlrev_b32_e32 v30, 16, v118
	v_mul_f32_e32 v10, v108, v2
	v_pk_mul_f32 v[4:5], v[12:13], v[0:1]
	v_fma_f32 v0, -v15, v15, 1.0
	v_rcp_f32_e32 v14, v14
	v_mul_f32_e32 v24, v27, v10
	v_fmac_f32_e32 v5, v4, v30
	v_sqrt_f32_e32 v4, v0
	v_mul_f32_e32 v0, v9, v24
	v_mul_f32_e32 v11, v11, v0
	v_mul_f32_e32 v12, v13, v11
	v_pk_mul_f32 v[8:9], v[14:15], v[4:5]
	v_mul_f32_e32 v4, v15, v12
	s_add_i32 s21, s21, s78
	v_lshlrev_b32_e32 v14, 10, v103
	v_lshlrev_b32_e32 v15, 1, v102
	v_lshlrev_b32_e32 v104, 16, v104
	v_add3_u32 v14, s21, v14, v15
	v_fmac_f32_e32 v9, v8, v104
	v_or_b32_e32 v13, v102, v184
	ds_read_u16 v15, v14 offset:49152
	ds_read_u16 v25, v14 offset:49216
	ds_read_u16 v26, v14 offset:49280
	ds_read_u16 v27, v14 offset:49344
	ds_read_u16 v28, v14 offset:49408
	ds_read_u16 v29, v14 offset:49472
	ds_read_u16 v30, v14 offset:49536
	ds_read_u16 v102, v14 offset:49600
	v_fma_f32 v8, v98, v4, v9
	v_lshlrev_b32_e32 v13, 2, v13
	s_waitcnt lgkmcnt(7)
	v_lshlrev_b32_e32 v15, 16, v15
	ds_bpermute_b32 v8, v13, v8
	v_mul_f32_e32 v103, 0xbfb8aa3b, v15
	v_exp_f32_e32 v103, v103
	s_add_i32 s7, s7, 32
	s_cmp_eq_u32 s55, s20
	s_waitcnt lgkmcnt(0)
	v_cndmask_b32_e32 v8, v8, v98, vcc
	v_add_f32_e32 v98, 1.0, v103
	v_rcp_f32_e32 v103, v98
	v_fmac_f32_e32 v9, v8, v4
	ds_bpermute_b32 v98, v13, v9 offset:128
	v_lshlrev_b32_e32 v13, 16, v25
	v_mul_f32_e32 v4, v103, v15
	v_mul_f32_e32 v15, 0xbfb8aa3b, v13
	v_exp_f32_e32 v15, v15
	v_fmac_f32_e32 v17, v16, v8
	v_mul_f32_e32 v4, v17, v4
	v_cvt_pk_bf16_f32 v4, v4, s0
	ds_write_b16 v14, v4 offset:49152
	v_add_f32_e32 v4, 1.0, v15
	v_lshlrev_b32_e32 v15, 16, v26
	v_mul_f32_e32 v16, 0xbfb8aa3b, v15
	v_rcp_f32_e32 v4, v4
	v_exp_f32_e32 v16, v16
	v_fmac_f32_e32 v31, v109, v8
	v_fmac_f32_e32 v117, v18, v8
	v_mul_f32_e32 v4, v4, v13
	v_add_f32_e32 v13, 1.0, v16
	v_rcp_f32_e32 v13, v13
	v_mul_f32_e32 v4, v31, v4
	v_cvt_pk_bf16_f32 v4, v4, s0
	ds_write_b16 v14, v4 offset:49216
	v_mul_f32_e32 v4, v13, v15
	v_lshlrev_b32_e32 v13, 16, v27
	v_mul_f32_e32 v15, 0xbfb8aa3b, v13
	v_exp_f32_e32 v15, v15
	v_mul_f32_e32 v4, v117, v4
	v_cvt_pk_bf16_f32 v4, v4, s0
	ds_write_b16 v14, v4 offset:49280
	v_add_f32_e32 v4, 1.0, v15
	v_lshlrev_b32_e32 v15, 16, v28
	v_mul_f32_e32 v16, 0xbfb8aa3b, v15
	v_rcp_f32_e32 v4, v4
	v_exp_f32_e32 v16, v16
	v_fmac_f32_e32 v110, v19, v8
	v_fmac_f32_e32 v111, v20, v8
	v_mul_f32_e32 v4, v4, v13
	v_add_f32_e32 v13, 1.0, v16
	v_rcp_f32_e32 v13, v13
	v_mul_f32_e32 v4, v110, v4
	v_cvt_pk_bf16_f32 v4, v4, s0
	ds_write_b16 v14, v4 offset:49344
	v_mul_f32_e32 v4, v13, v15
	v_lshlrev_b32_e32 v13, 16, v29
	v_mul_f32_e32 v15, 0xbfb8aa3b, v13
	v_exp_f32_e32 v15, v15
	v_mul_f32_e32 v4, v111, v4
	v_cvt_pk_bf16_f32 v4, v4, s0
	ds_write_b16 v14, v4 offset:49408
	v_add_f32_e32 v4, 1.0, v15
	v_lshlrev_b32_e32 v15, 16, v30
	v_mul_f32_e32 v16, 0xbfb8aa3b, v15
	v_rcp_f32_e32 v4, v4
	v_exp_f32_e32 v16, v16
	v_fmac_f32_e32 v112, v21, v8
	v_fmac_f32_e32 v107, v6, v8
	v_mul_f32_e32 v4, v4, v13
	v_add_f32_e32 v13, 1.0, v16
	v_rcp_f32_e32 v13, v13
	v_mul_f32_e32 v4, v112, v4
	v_cvt_pk_bf16_f32 v4, v4, s0
	v_lshlrev_b32_e32 v6, 16, v102
	ds_write_b16 v14, v4 offset:49472
	v_mul_f32_e32 v4, v13, v15
	v_mul_f32_e32 v13, 0xbfb8aa3b, v6
	v_exp_f32_e32 v13, v13
	v_mul_f32_e32 v4, v107, v4
	v_cvt_pk_bf16_f32 v4, v4, s0
	ds_write_b16 v14, v4 offset:49536
	v_add_f32_e32 v4, 1.0, v13
	ds_read_u16 v13, v14 offset:49664
	ds_read_u16 v15, v14 offset:49728
	ds_read_u16 v16, v14 offset:49792
	ds_read_u16 v17, v14 offset:49856
	ds_read_u16 v18, v14 offset:49920
	ds_read_u16 v19, v14 offset:49984
	ds_read_u16 v20, v14 offset:50048
	ds_read_u16 v21, v14 offset:50112
	s_waitcnt lgkmcnt(7)
	v_lshlrev_b32_e32 v13, 16, v13
	v_mul_f32_e32 v25, 0xbfb8aa3b, v13
	v_rcp_f32_e32 v4, v4
	v_exp_f32_e32 v25, v25
	v_fmac_f32_e32 v114, v22, v8
	v_fmac_f32_e32 v113, v23, v8
	v_mul_f32_e32 v4, v4, v6
	v_add_f32_e32 v6, 1.0, v25
	v_rcp_f32_e32 v6, v6
	v_mul_f32_e32 v4, v114, v4
	v_cvt_pk_bf16_f32 v4, v4, s0
	ds_write_b16 v14, v4 offset:49600
	v_mul_f32_e32 v4, v6, v13
	s_waitcnt lgkmcnt(7)
	v_lshlrev_b32_e32 v6, 16, v15
	v_mul_f32_e32 v13, 0xbfb8aa3b, v6
	v_exp_f32_e32 v13, v13
	v_mul_f32_e32 v4, v113, v4
	v_cvt_pk_bf16_f32 v4, v4, s0
	ds_write_b16 v14, v4 offset:49664
	v_add_f32_e32 v4, 1.0, v13
	s_waitcnt lgkmcnt(7)
	v_lshlrev_b32_e32 v13, 16, v16
	v_mul_f32_e32 v15, 0xbfb8aa3b, v13
	v_rcp_f32_e32 v4, v4
	v_exp_f32_e32 v15, v15
	v_fmac_f32_e32 v105, v2, v8
	v_fmac_f32_e32 v106, v10, v8
	v_mul_f32_e32 v2, v4, v6
	v_add_f32_e32 v4, 1.0, v15
	v_rcp_f32_e32 v4, v4
	v_mul_f32_e32 v2, v105, v2
	v_cvt_pk_bf16_f32 v2, v2, s0
	ds_write_b16 v14, v2 offset:49728
	v_mul_f32_e32 v2, v4, v13
	s_waitcnt lgkmcnt(7)
	v_lshlrev_b32_e32 v4, 16, v17
	v_mul_f32_e32 v6, 0xbfb8aa3b, v4
	v_exp_f32_e32 v6, v6
	v_mul_f32_e32 v2, v106, v2
	v_cvt_pk_bf16_f32 v2, v2, s0
	ds_write_b16 v14, v2 offset:49792
	v_add_f32_e32 v2, 1.0, v6
	s_waitcnt lgkmcnt(7)
	v_lshlrev_b32_e32 v6, 16, v18
	v_mul_f32_e32 v10, 0xbfb8aa3b, v6
	v_rcp_f32_e32 v2, v2
	v_exp_f32_e32 v10, v10
	v_fmac_f32_e32 v7, v24, v8
	v_fmac_f32_e32 v3, v0, v8
	v_mul_f32_e32 v2, v2, v4
	v_add_f32_e32 v4, 1.0, v10
	v_rcp_f32_e32 v4, v4
	v_mul_f32_e32 v2, v7, v2
	v_cvt_pk_bf16_f32 v2, v2, s0
	ds_write_b16 v14, v2 offset:49856
	v_mul_f32_e32 v0, v4, v6
	s_waitcnt lgkmcnt(7)
	v_lshlrev_b32_e32 v2, 16, v19
	v_mul_f32_e32 v0, v3, v0
	v_mul_f32_e32 v3, 0xbfb8aa3b, v2
	v_exp_f32_e32 v3, v3
	v_cvt_pk_bf16_f32 v0, v0, s0
	ds_write_b16 v14, v0 offset:49920
	v_fmac_f32_e32 v1, v8, v11
	v_add_f32_e32 v0, 1.0, v3
	s_waitcnt lgkmcnt(7)
	v_lshlrev_b32_e32 v3, 16, v20
	v_rcp_f32_e32 v0, v0
	v_mul_f32_e32 v4, 0xbfb8aa3b, v3
	v_exp_f32_e32 v4, v4
	v_fmac_f32_e32 v5, v8, v12
	v_mul_f32_e32 v0, v0, v2
	s_waitcnt lgkmcnt(6)
	v_lshlrev_b32_e32 v2, 16, v21
	v_mul_f32_e32 v0, v1, v0
	v_add_f32_e32 v1, 1.0, v4
	v_mul_f32_e32 v4, 0xbfb8aa3b, v2
	v_rcp_f32_e32 v1, v1
	v_exp_f32_e32 v4, v4
	v_cvt_pk_bf16_f32 v0, v0, s0
	ds_write_b16 v14, v0 offset:49984
	v_mul_f32_e32 v0, v1, v3
	v_add_f32_e32 v1, 1.0, v4
	v_rcp_f32_e32 v1, v1
	v_mul_f32_e32 v0, v5, v0
	v_cvt_pk_bf16_f32 v0, v0, s0
	ds_write_b16 v14, v0 offset:50048
	v_mul_f32_e32 v0, v1, v2
	v_mul_f32_e32 v0, v9, v0
	v_cvt_pk_bf16_f32 v0, v0, s0
	ds_write_b16 v14, v0 offset:50112
	s_waitcnt vmcnt(0) lgkmcnt(0)
	s_barrier
	s_cbranch_scc1 .LBB0_589
	s_mov_b32 s21, s20
	s_cmp_eq_u32 s21, 0
	s_cselect_b64 s[4:5], -1, 0
	s_and_b64 vcc, exec, s[4:5]
	s_cbranch_vccz .LBB0_584
	s_branch .LBB0_585
